# P5->P6 seam: edge rows via atomic swaps + sc1 loads, wait only for own and neighbour quad (same-XCC mode)
# baseline (speedup 1.0000x reference)
; #define LAS __attribute__((address_space(3)))
;     __device__ __forceinline__ void run(f32x4 (&acc)[2][2][4][2], const pg8::Unit& u, int wr, int wc, int fr_, int fq_, int buf) const {
;     ...
;             for (int ai = 0; ai < 2; ++ai) { const f32x4 q = *(const LAS f32x4*)(T + 128 * ai + 64 * wr + 4 * fr);
;                 rs[ai][0] = rsqrtf(q[0] * (1.0f / D) + EPS); rs[ai][1] = rsqrtf(q[1] * (1.0f / D) + EPS); rs[ai][2] = rsqrtf(q[2] * (1.0f / D) + EPS); rs[ai][3] = rsqrtf(q[3] * (1.0f / D) + EPS); }
; #pragma unroll
;             for (int bj = 0; bj < 2; ++bj)
; #pragma unroll
;                 for (int n = 0; n < 2; ++n) { const f32x4 c2v = *(const LAS f32x4*)(T + 256 + 128 * bj + colL + 4 * n);
; #pragma unroll
;                     for (int ai = 0; ai < 2; ++ai)
; #pragma unroll
;                         for (int m = 0; m < 4; ++m) acc[ai][bj][m][n] = acc[ai][bj][m][n] * rs[ai][m] + c2v; } }
;         if (fr == 0 || fr == 15) {
;             const bool lastr = fr == 15;
;             LAS float* xb = X + (lastr ? 256 : 0) + colL;
; #pragma unroll
;             for (int bj = 0; bj < 2; ++bj)
; #pragma unroll
;                 for (int n = 0; n < 2; ++n)
; #pragma unroll
;                     for (int ai = 0; ai < 2; ++ai) { const int rb = 2 * ai + wr; f32x4 v;
; #pragma unroll
;                         for (int e = 0; e < 4; ++e) v[e] = lastr ? acc[ai][bj][3][n][e] : acc[ai][bj][0][n][e];
;                         *(LAS f32x4*)(xb + rb * 512 + 128 * bj + 4 * n) = v; }
;         }
;         asm volatile("s_waitcnt lgkmcnt(0)" ::: "memory"); __builtin_amdgcn_s_barrier(); asm volatile("" ::: "memory");
;         if (wr == 0 && fr == 0) {
; #pragma unroll
;             for (int bj = 0; bj < 2; ++bj)
; #pragma unroll
;                 for (int n = 0; n < 2; ++n) { float* ep = edge + ((size_t)gpm * 4 + 0) * FF2 + colg + 128 * bj + 4 * n; *(f32x4*)ep = acc[0][bj][0][n]; *(f32x4*)(ep + FF2) = acc[0][bj][1][n]; }
;         }
;         if (wr == 1 && fr == 15) {
; #pragma unroll
;             for (int bj = 0; bj < 2; ++bj)
; #pragma unroll
;                 for (int n = 0; n < 2; ++n) { float* ep = edge + ((size_t)gpm * 4 + 2) * FF2 + colg + 128 * bj + 4 * n; *(f32x4*)ep = acc[1][bj][2][n]; *(f32x4*)(ep + FF2) = acc[1][bj][3][n]; }
;         }
.LBB0_541:
	s_or_b64 exec, exec, s[2:3]
	v_fmamk_f32 v82, v151, 0x3a800000, v233
	v_mul_f32_e32 v83, 0x4b800000, v82
	v_cmp_gt_f32_e32 vcc, s81, v82
	s_waitcnt lgkmcnt(0)
	s_barrier
	s_add_i32 s5, s54, s70
	v_cndmask_b32_e32 v82, v82, v83, vcc
	v_rsq_f32_e32 v83, v82
	v_lshl_add_u32 v82, s52, 8, v146
	s_mul_hi_i32 s4, s5, 0x16000
	s_mul_i32 s5, s5, 0x16000
	v_mul_f32_e32 v84, 0x45800000, v83
	v_cndmask_b32_e32 v84, v83, v84, vcc
	v_pk_fma_f32 v[98:99], v[70:71], v[84:85], v[134:135] op_sel_hi:[1,0,1]
	v_or_b32_e32 v70, s14, v236
	v_pk_fma_f32 v[104:105], v[80:81], v[84:85], v[144:145] op_sel_hi:[1,0,1]
	v_pk_fma_f32 v[102:103], v[78:79], v[84:85], v[142:143] op_sel_hi:[1,0,1]
	v_pk_fma_f32 v[76:77], v[76:77], v[84:85], v[140:141] op_sel_hi:[1,0,1]
	v_pk_fma_f32 v[74:75], v[74:75], v[84:85], v[138:139] op_sel_hi:[1,0,1]
	v_pk_fma_f32 v[100:101], v[72:73], v[84:85], v[136:137] op_sel_hi:[1,0,1]
	v_pk_fma_f32 v[68:69], v[68:69], v[84:85], v[132:133] op_sel_hi:[1,0,1]
	v_pk_fma_f32 v[66:67], v[66:67], v[84:85], v[130:131] op_sel_hi:[1,0,1]
	v_cmp_eq_u32_e32 vcc, 0, v70
	v_ashrrev_i32_e32 v83, 31, v82
	s_and_saveexec_b64 s[2:3], vcc
	s_cbranch_execz .LBB0_543
	s_add_u32 s6, s22, s5
	s_addc_u32 s7, s23, s4
	v_lshl_add_u64 v[70:71], v[82:83], 2, s[6:7]
	v_add_co_u32_e32 v72, vcc, 0x5000, v70
	global_atomic_swap_x2 v[70:71], v[118:119], off
	global_atomic_swap_x2 v[70:71], v[120:121], off offset:8
	s_nop 0
	v_addc_co_u32_e32 v73, vcc, 0, v71, vcc
	global_atomic_swap_x2 v[72:73], v[102:103], off offset:2048
	global_atomic_swap_x2 v[72:73], v[104:105], off offset:2056
	global_atomic_swap_x2 v[70:71], v[94:95], off offset:16
	global_atomic_swap_x2 v[70:71], v[96:97], off offset:24
	global_atomic_swap_x2 v[72:73], v[74:75], off offset:2064
	global_atomic_swap_x2 v[72:73], v[76:77], off offset:2072
	global_atomic_swap_x2 v[70:71], v[106:107], off offset:512
	global_atomic_swap_x2 v[70:71], v[108:109], off offset:520
	global_atomic_swap_x2 v[72:73], v[98:99], off offset:2560
	global_atomic_swap_x2 v[72:73], v[100:101], off offset:2568
	global_atomic_swap_x2 v[70:71], v[86:87], off offset:528
	global_atomic_swap_x2 v[70:71], v[88:89], off offset:536
	global_atomic_swap_x2 v[72:73], v[66:67], off offset:2576
	global_atomic_swap_x2 v[72:73], v[68:69], off offset:2584
.LBB0_543:
	s_or_b64 exec, exec, s[2:3]
	v_fmamk_f32 v70, v148, 0x3a800000, v233
	v_mul_f32_e32 v71, 0x4b800000, v70
	v_cmp_gt_f32_e32 vcc, s81, v70
	s_and_b64 s[2:3], s[26:27], s[0:1]
	s_nop 0
	v_cndmask_b32_e32 v70, v70, v71, vcc
	v_rsq_f32_e32 v70, v70
	s_nop 0
	v_mul_f32_e32 v71, 0x45800000, v70
	v_cndmask_b32_e32 v70, v70, v71, vcc
	v_pk_fma_f32 v[48:49], v[48:49], v[70:71], v[144:145] op_sel_hi:[1,0,1]
	v_pk_fma_f32 v[46:47], v[46:47], v[70:71], v[142:143] op_sel_hi:[1,0,1]
	v_pk_fma_f32 v[64:65], v[64:65], v[70:71], v[140:141] op_sel_hi:[1,0,1]
	v_pk_fma_f32 v[62:63], v[62:63], v[70:71], v[138:139] op_sel_hi:[1,0,1]
	v_pk_fma_f32 v[32:33], v[32:33], v[70:71], v[136:137] op_sel_hi:[1,0,1]
	v_pk_fma_f32 v[30:31], v[30:31], v[70:71], v[134:135] op_sel_hi:[1,0,1]
	v_pk_fma_f32 v[52:53], v[52:53], v[70:71], v[132:133] op_sel_hi:[1,0,1]
	v_pk_fma_f32 v[50:51], v[50:51], v[70:71], v[130:131] op_sel_hi:[1,0,1]
	s_and_saveexec_b64 s[0:1], s[2:3]
	s_cbranch_execz .LBB0_545
	s_add_u32 s2, s22, s5
	s_addc_u32 s3, s23, s4
	v_lshl_add_u64 v[70:71], v[82:83], 2, s[2:3]
	v_add_co_u32_e32 v72, vcc, 0xb000, v70
	s_nop 1
	v_addc_co_u32_e32 v73, vcc, 0, v71, vcc
	v_add_co_u32_e32 v70, vcc, 0x10000, v70
	global_atomic_swap_x2 v[72:73], v[46:47], off
	global_atomic_swap_x2 v[72:73], v[48:49], off offset:8
	s_nop 0
	v_addc_co_u32_e32 v71, vcc, 0, v71, vcc
	global_atomic_swap_x2 v[70:71], v[2:3], off offset:2048
	global_atomic_swap_x2 v[70:71], v[4:5], off offset:2056
	global_atomic_swap_x2 v[72:73], v[62:63], off offset:16
	global_atomic_swap_x2 v[72:73], v[64:65], off offset:24
	global_atomic_swap_x2 v[70:71], v[18:19], off offset:2064
	global_atomic_swap_x2 v[70:71], v[20:21], off offset:2072
	global_atomic_swap_x2 v[72:73], v[30:31], off offset:512
	global_atomic_swap_x2 v[72:73], v[32:33], off offset:520
	global_atomic_swap_x2 v[70:71], v[6:7], off offset:2560
	global_atomic_swap_x2 v[70:71], v[8:9], off offset:2568
	global_atomic_swap_x2 v[72:73], v[50:51], off offset:528
	global_atomic_swap_x2 v[72:73], v[52:53], off offset:536
	global_atomic_swap_x2 v[70:71], v[22:23], off offset:2576
	global_atomic_swap_x2 v[70:71], v[24:25], off offset:2584

; __device__ __forceinline__ unsigned xb_ld(unsigned* p)              { return __hip_atomic_load(p, __ATOMIC_RELAXED, __HIP_MEMORY_SCOPE_AGENT); }
; __device__ __forceinline__ void xcd_barrier(const XcdBarrier& b) {
;     asm volatile("s_waitcnt vmcnt(0)" ::: "memory");
;     __syncthreads();
;     if (threadIdx.x == 0) {
;         unsigned* bar = b.bar;
;         __builtin_amdgcn_s_waitcnt(0);
;         unsigned nloc = b.st[0], nx = b.st[1];
;         if (nloc == 0u) { xcd_barrier_complete(bar, b.x, b.gsize, nloc, nx); b.st[0] = nloc; b.st[1] = nx; }
;         const unsigned old = xb_add(&bar[XB_XSUB(b.x)], 1u);
;         const unsigned gen = old / nloc;
;         if (old + 1u == (gen + 1u) * nloc) {
;             __builtin_amdgcn_fence(__ATOMIC_RELEASE, "agent");
;             asm volatile("s_waitcnt vmcnt(0)" ::: "memory");
;             const unsigned og = xb_add(&bar[XB_TOP], 1u);
;             const unsigned tg = og / nx;
;             if (og + 1u == (tg + 1u) * nx) xb_add(&bar[XB_TOPGEN], 1u);
;             else XB_SPIN(xb_ld(&bar[XB_TOPGEN]) == tg, bar);
;             __builtin_amdgcn_fence(__ATOMIC_ACQUIRE, "agent");
;             xb_add(&bar[XB_XGEN(b.x)], 1u);
;             asm volatile("s_waitcnt vmcnt(0)" ::: "memory");
;         } else {
;             XB_SPIN(xb_ld(&bar[XB_XGEN(b.x)]) == gen, bar);
;             __builtin_amdgcn_fence(__ATOMIC_ACQUIRE, "agent");
;             asm volatile("s_waitcnt vmcnt(0)" ::: "memory");
;         }
;     }
;     __syncthreads();
; }
; __global__ void __launch_bounds__(NWAVES * 64, 2) fwd(Args a) {
;     ...
;         for (int idx = (xh * cph + gk) * 512 + tid; idx < 2 * GPANELS * (FF / 8); idx += gsz * 512) {
;             const int br = idx / (FF / 8), f = 8 * (idx % (FF / 8)), gcol = (f >> 7) * 256 + (f & 127);
;             const int pm = pm0 + (br >> 1), last = br & 1, row = pm * 256 + (last ? 255 : 0);
;             const int b = batch_of_row(row), t = row < NPR ? (row & 2047) : ((row - NPR) & 8191), T = b < 8 ? 2048 : 8192;
;             const float* em; const float* e0; const float* ep;
;             if (!last) { em = EDGE + ((size_t)(pm - 1) * 4 + 3) * FF2; e0 = EDGE + ((size_t)pm * 4 + 0) * FF2; ep = EDGE + ((size_t)pm * 4 + 1) * FF2; }
;             else       { em = EDGE + ((size_t)pm * 4 + 2) * FF2; e0 = EDGE + ((size_t)pm * 4 + 3) * FF2; ep = EDGE + ((size_t)(pm + 1) * 4 + 0) * FF2; }
.LBB0_562:
	s_setprio 0
	s_waitcnt vmcnt(0)
	s_waitcnt vmcnt(0) lgkmcnt(0)
	s_barrier
	s_and_saveexec_b64 s[0:1], s[90:91]
	v_readlane_b32 s42, v250, 18
	s_xor_b64 s[0:1], exec, s[0:1]
	v_readlane_b32 s43, v250, 19
	s_cbranch_execz .LBB0_615
	s_cmp_lg_u32 s100, 0
	s_cbranch_scc1 .Lq5_slow
	v_readlane_b32 s4, v250, 14
	v_readlane_b32 s5, v250, 15
	s_and_b32 s6, s101, 7
	s_lshl_b32 s6, s6, 3
	s_bfe_u32 s7, s101, 0x30003
	s_or_b32 s6, s6, s7
	s_lshl_b32 s6, s6, 7
	s_add_i32 s6, s6, 0x1d000
	v_mov_b32_e32 v1, s6
	v_mov_b32_e32 v2, 1
	s_mov_b32 s9, 0
	s_nop 4
	global_atomic_add v1, v2, s[4:5]
	buffer_inv sc1
.Lq5a_spin:
	global_load_dword v3, v1, s[4:5] sc1
	s_waitcnt vmcnt(0)
	v_cmp_gt_u32_e32 vcc, 4, v3
	s_cbranch_vccz .Lq5a_ok
	s_sleep 1
	s_add_i32 s9, s9, 1
	s_cmp_lt_u32 s9, 0x2000
	s_cbranch_scc1 .Lq5a_spin
.Lq5a_ok:
	s_and_b32 s6, s101, 1
	s_lshl_b32 s6, s6, 4
	s_bfe_u32 s7, s101, 0x30003
	s_add_i32 s6, s6, s7
	s_bfe_u32 s7, s101, 0x10007
	s_lshl_b32 s7, s7, 3
	s_add_i32 s6, s6, s7
	s_bfe_u32 s7, s101, 0x10006
	s_lshl_b32 s7, s7, 1
	s_add_i32 s6, s6, s7
	s_add_i32 s6, s6, -1
	s_andn2_b32 s7, s6, 31
	s_cmp_eq_u32 s7, 0
	s_cbranch_scc0 .LBB0_615
	s_lshr_b32 s7, s6, 4
	s_and_b32 s6, s6, 7
	s_and_b32 s8, s101, 6
	s_or_b32 s7, s7, s8
	s_lshl_b32 s7, s7, 3
	s_or_b32 s6, s6, s7
	s_lshl_b32 s6, s6, 7
	s_add_i32 s6, s6, 0x1d000
	v_mov_b32_e32 v1, s6
	s_mov_b32 s9, 0

; __global__ void __launch_bounds__(NWAVES * 64, 2) fwd(Args a) {
;     ...
;             const int br = idx / (FF / 8), f = 8 * (idx % (FF / 8)), gcol = (f >> 7) * 256 + (f & 127);
;             const int pm = pm0 + (br >> 1), last = br & 1, row = pm * 256 + (last ? 255 : 0);
;             const int b = batch_of_row(row), t = row < NPR ? (row & 2047) : ((row - NPR) & 8191), T = b < 8 ? 2048 : 8192;
;             const float* em; const float* e0; const float* ep;
;             if (!last) { em = EDGE + ((size_t)(pm - 1) * 4 + 3) * FF2; e0 = EDGE + ((size_t)pm * 4 + 0) * FF2; ep = EDGE + ((size_t)pm * 4 + 1) * FF2; }
;             else       { em = EDGE + ((size_t)pm * 4 + 2) * FF2; e0 = EDGE + ((size_t)pm * 4 + 3) * FF2; ep = EDGE + ((size_t)(pm + 1) * 4 + 0) * FF2; }
;             const bool hm = t > 0, hp = t < T - 1;
;             float res[2][8];
; #pragma unroll
;             for (int part = 0; part < 2; ++part) {
;                 const int col = gcol + 128 * part;
; #pragma unroll
;                 for (int hh = 0; hh < 2; ++hh) {
;                     const int c = col + 4 * hh; const f32x4 zero = {0.f, 0.f, 0.f, 0.f};
;                     const f32x4 um = hm ? *(const f32x4*)(em + c) : zero, u0 = *(const f32x4*)(e0 + c), up = hp ? *(const f32x4*)(ep + c) : zero;
;                     const f32x4 w0 = *(const f32x4*)(convp + c), w1 = *(const f32x4*)(convp + FF2 + c), w2 = *(const f32x4*)(convp + 2 * FF2 + c), cb = *(const f32x4*)(cbp + c);
;                     const f32x4 r = w0 * um + w1 * u0 + w2 * up + cb;
;                     res[part][4 * hh + 0] = r[0]; res[part][4 * hh + 1] = r[1]; res[part][4 * hh + 2] = r[2]; res[part][4 * hh + 3] = r[3];
;                 }
.LBB0_618:
	v_mul_hi_i32 v2, v1, s15
	v_lshrrev_b32_e32 v3, 31, v2
	v_ashrrev_i32_e32 v2, 6, v2
	v_add_u32_e32 v8, v2, v3
	v_ashrrev_i32_e32 v2, 1, v8
	v_add_u32_e32 v14, s70, v2
	v_and_b32_e32 v2, 1, v8
	v_cmp_eq_u32_e32 vcc, 0, v2
	v_cmp_eq_u32_e64 s[0:1], 1, v2
	v_mul_hi_i32_i24_e32 v3, 0x16000, v14
	v_mul_i32_i24_e32 v2, 0x16000, v14
	s_and_saveexec_b64 s[2:3], s[0:1]
	s_xor_b64 s[0:1], exec, s[2:3]
	v_lshl_add_u64 v[2:3], s[22:23], 0, v[2:3]
	v_lshl_add_u64 v[6:7], v[2:3], 0, s[24:25]
	v_lshl_add_u64 v[10:11], v[2:3], 0, s[26:27]
	v_add_u32_e32 v4, 1, v14
	v_mov_b64_e32 v[2:3], s[22:23]
	v_mad_i64_i32 v[4:5], s[2:3], v4, s30, v[2:3]
	s_andn2_saveexec_b64 s[0:1], s[0:1]
	v_add_u32_e32 v6, -1, v14
	v_mov_b64_e32 v[4:5], s[22:23]
	v_mad_i64_i32 v[4:5], s[2:3], v6, s30, v[4:5]
	v_lshl_add_u64 v[10:11], s[22:23], 0, v[2:3]
	v_lshl_add_u64 v[6:7], v[4:5], 0, s[26:27]
	v_lshl_add_u64 v[4:5], v[10:11], 0, s[28:29]
	s_or_b64 exec, exec, s[0:1]
	v_mul_i32_i24_e32 v111, 0x160, v8
	v_lshlrev_b32_e32 v2, 3, v111
	v_sub_u32_e32 v98, v104, v2
	v_lshlrev_b32_e32 v2, 4, v111
	v_sub_u32_e32 v2, v105, v2
	v_and_b32_e32 v3, 0x78, v98
	v_lshlrev_b32_e32 v110, 8, v14
	v_cndmask_b32_e64 v109, v106, 0, vcc
	v_and_or_b32 v100, v2, s31, v3
	v_or_b32_e32 v2, v110, v109
	v_cmp_gt_i32_e64 s[0:1], s33, v2
	v_ashrrev_i32_e32 v101, 31, v100
	v_lshl_add_u64 v[40:41], v[100:101], 2, v[6:7]
	v_cndmask_b32_e64 v2, v107, v108, s[0:1]
	v_bitop3_b32 v3, v2, v110, v109 bitop3:0xe0
	v_cmp_ne_u32_e32 vcc, 0, v3
	v_mov_b32_e32 v2, 0
	v_mov_b32_e32 v6, 0
	v_mov_b32_e32 v7, 0
	v_mov_b32_e32 v8, 0
	v_mov_b32_e32 v9, 0
	s_and_saveexec_b64 s[2:3], vcc
	s_cbranch_execz .LBB0_624
	global_load_dwordx4 v[6:9], v[40:41], off sc1
.LBB0_624:
	s_or_b64 exec, exec, s[2:3]
	v_lshl_add_u64 v[50:51], v[100:101], 2, v[10:11]
	global_load_dwordx4 v[10:13], v[50:51], off sc1
	v_cmp_gt_i32_e64 s[2:3], 64, v14
	s_and_b64 s[0:1], s[0:1], s[2:3]
	v_cndmask_b32_e64 v14, v107, v108, s[0:1]
	v_cmp_lt_u32_e64 s[0:1], v3, v14
	v_lshl_add_u64 v[102:103], v[100:101], 2, v[4:5]
	v_mov_b32_e32 v3, 0
	v_mov_b32_e32 v4, 0
	v_mov_b32_e32 v5, 0
	s_and_saveexec_b64 s[2:3], s[0:1]
	s_cbranch_execz .LBB0_626
	global_load_dwordx4 v[2:5], v[102:103], off sc1
.LBB0_626:
	s_or_b64 exec, exec, s[2:3]
	v_lshlrev_b64 v[14:15], 2, v[100:101]
	v_lshl_add_u64 v[16:17], s[42:43], 0, v[14:15]
	v_lshl_add_u64 v[18:19], s[6:7], 0, v[14:15]
	global_load_dwordx4 v[22:25], v[16:17], off
	global_load_dwordx4 v[30:33], v[18:19], off
	v_lshl_add_u64 v[16:17], s[8:9], 0, v[14:15]
	v_lshl_add_u64 v[14:15], s[44:45], 0, v[14:15]
	global_load_dwordx4 v[18:21], v[16:17], off
	s_nop 0
	global_load_dwordx4 v[14:17], v[14:15], off
	v_mov_b32_e32 v26, 0
	v_mov_b32_e32 v34, 0
	v_mov_b32_e32 v35, 0
	v_mov_b32_e32 v36, 0
	v_mov_b32_e32 v37, 0
	s_and_saveexec_b64 s[2:3], vcc
	s_cbranch_execz .LBB0_628
	global_load_dwordx4 v[34:37], v[40:41], off offset:16 sc1
.LBB0_628:
	s_or_b64 exec, exec, s[2:3]
	global_load_dwordx4 v[46:49], v[50:51], off offset:16 sc1
	v_mov_b32_e32 v27, 0
	v_mov_b32_e32 v28, 0
	v_mov_b32_e32 v29, 0
	s_and_saveexec_b64 s[2:3], s[0:1]
	s_cbranch_execz .LBB0_630
	global_load_dwordx4 v[26:29], v[102:103], off offset:16 sc1
.LBB0_630:
	s_or_b64 exec, exec, s[2:3]
	v_or_b32_e32 v38, 4, v100
	v_ashrrev_i32_e32 v39, 31, v38
	v_lshlrev_b64 v[38:39], 2, v[38:39]
	v_lshl_add_u64 v[42:43], s[42:43], 0, v[38:39]
	v_lshl_add_u64 v[44:45], s[6:7], 0, v[38:39]
	global_load_dwordx4 v[62:65], v[42:43], off
	global_load_dwordx4 v[70:73], v[44:45], off
	v_lshl_add_u64 v[42:43], s[8:9], 0, v[38:39]
	v_lshl_add_u64 v[38:39], s[44:45], 0, v[38:39]
	global_load_dwordx4 v[58:61], v[42:43], off
	global_load_dwordx4 v[54:57], v[38:39], off
	v_mov_b32_e32 v66, 0
	v_mov_b32_e32 v74, 0
	v_mov_b32_e32 v75, 0
	v_mov_b32_e32 v76, 0
	v_mov_b32_e32 v77, 0
	s_and_saveexec_b64 s[2:3], vcc
	s_cbranch_execz .LBB0_632
	global_load_dwordx4 v[74:77], v[40:41], off offset:512 sc1
.LBB0_632:
	s_or_b64 exec, exec, s[2:3]
	global_load_dwordx4 v[78:81], v[50:51], off offset:512 sc1
	v_mov_b32_e32 v67, 0
	v_mov_b32_e32 v68, 0
	v_mov_b32_e32 v69, 0
	s_and_saveexec_b64 s[2:3], s[0:1]
	s_cbranch_execz .LBB0_634
	global_load_dwordx4 v[66:69], v[102:103], off offset:512 sc1
.LBB0_634:
	s_or_b64 exec, exec, s[2:3]
	v_or_b32_e32 v38, 0x80, v100
	v_ashrrev_i32_e32 v39, 31, v38
	v_lshlrev_b64 v[38:39], 2, v[38:39]
	v_lshl_add_u64 v[42:43], s[42:43], 0, v[38:39]
	v_lshl_add_u64 v[44:45], s[6:7], 0, v[38:39]
	global_load_dwordx4 v[90:93], v[42:43], off
	global_load_dwordx4 v[94:97], v[44:45], off
	v_lshl_add_u64 v[42:43], s[8:9], 0, v[38:39]
	v_lshl_add_u64 v[38:39], s[44:45], 0, v[38:39]
	global_load_dwordx4 v[86:89], v[42:43], off
	global_load_dwordx4 v[82:85], v[38:39], off
	v_mov_b32_e32 v38, 0
	v_mov_b32_e32 v42, 0
	v_mov_b32_e32 v43, 0
	v_mov_b32_e32 v44, 0
	v_mov_b32_e32 v45, 0
	s_and_saveexec_b64 s[2:3], vcc
	s_cbranch_execz .LBB0_636
	global_load_dwordx4 v[42:45], v[40:41], off offset:528 sc1
.LBB0_636:
	s_or_b64 exec, exec, s[2:3]
	global_load_dwordx4 v[50:53], v[50:51], off offset:528 sc1
	v_mov_b32_e32 v39, 0
	v_mov_b32_e32 v40, 0
	v_mov_b32_e32 v41, 0
	s_and_saveexec_b64 s[2:3], s[0:1]
	s_cbranch_execz .LBB0_617
	global_load_dwordx4 v[38:41], v[102:103], off offset:528 sc1
	s_branch .LBB0_617
